# final RMSNorm: six-hop ds_bpermute row all-reduce replaced by DPP row ops + permlane16/32 swaps
# speedup vs baseline: 1.0011x; 1.0011x over previous
.LBB0_1127:
	s_add_i32 s10, s9, 1
	s_cmpk_lt_i32 s8, 0x4000
	s_waitcnt vmcnt(4)
	v_lshlrev_b32_e32 v32, 16, v76
	v_and_b32_e32 v33, 0xffff0000, v76
	v_lshlrev_b32_e32 v30, 16, v83
	v_and_b32_e32 v31, 0xffff0000, v83
	v_lshlrev_b32_e32 v14, 16, v77
	v_and_b32_e32 v15, 0xffff0000, v77
	v_lshlrev_b32_e32 v40, 16, v82
	v_and_b32_e32 v41, 0xffff0000, v82
	v_lshlrev_b32_e32 v34, 16, v78
	v_and_b32_e32 v35, 0xffff0000, v78
	v_lshlrev_b32_e32 v16, 16, v79
	v_and_b32_e32 v17, 0xffff0000, v79
	v_lshlrev_b32_e32 v36, 16, v80
	v_and_b32_e32 v37, 0xffff0000, v80
	v_lshlrev_b32_e32 v38, 16, v81
	v_and_b32_e32 v39, 0xffff0000, v81
	global_load_dwordx4 v[76:79], v[2:3], off
	global_load_dwordx4 v[80:83], v[2:3], off offset:1024
	v_lshl_add_u64 v[2:3], v[2:3], 0, s[4:5]
	v_pk_mul_f32 v[20:21], v[32:33], v[32:33]
	v_pk_mul_f32 v[42:43], v[14:15], v[14:15]
	v_add_f32_e32 v20, v20, v21
	v_add_f32_e32 v20, v20, v42
	v_pk_mul_f32 v[44:45], v[34:35], v[34:35]
	v_add_f32_e32 v20, v20, v43
	v_add_f32_e32 v20, v20, v44
	v_pk_mul_f32 v[46:47], v[16:17], v[16:17]
	v_add_f32_e32 v20, v20, v45
	v_add_f32_e32 v20, v20, v46
	v_pk_mul_f32 v[48:49], v[36:37], v[36:37]
	v_add_f32_e32 v20, v20, v47
	v_add_f32_e32 v20, v20, v48
	v_pk_mul_f32 v[50:51], v[38:39], v[38:39]
	v_add_f32_e32 v20, v20, v49
	v_add_f32_e32 v20, v20, v50
	v_pk_mul_f32 v[52:53], v[40:41], v[40:41]
	v_add_f32_e32 v20, v20, v51
	v_add_f32_e32 v20, v20, v52
	v_pk_mul_f32 v[18:19], v[30:31], v[30:31]
	v_add_f32_e32 v20, v20, v53
	v_add_f32_e32 v18, v20, v18
	v_add_f32_e32 v18, v18, v19
	s_nop 1
	v_add_f32_dpp v19, v18, v18 quad_perm:[1,0,3,2] row_mask:0xf bank_mask:0xf
	s_nop 1
	v_add_f32_dpp v18, v19, v19 quad_perm:[2,3,0,1] row_mask:0xf bank_mask:0xf
	s_nop 1
	v_add_f32_dpp v19, v18, v18 row_half_mirror row_mask:0xf bank_mask:0xf
	s_nop 1
	v_add_f32_dpp v18, v19, v19 row_ror:8 row_mask:0xf bank_mask:0xf
	v_mov_b32_e32 v19, v18
	s_nop 1
	v_permlane16_swap_b32_e32 v19, v18
	v_add_f32_e32 v18, v19, v18
	v_mov_b32_e32 v19, v18
	s_nop 1
	v_permlane32_swap_b32_e32 v19, v18
	v_add_f32_e32 v18, v19, v18
	v_fmamk_f32 v18, v18, 0x3a800000, v12
	v_mul_f32_e32 v19, 0x4f800000, v18
	v_cmp_gt_f32_e32 vcc, s3, v18
	s_nop 1
	v_cndmask_b32_e32 v18, v18, v19, vcc
	v_sqrt_f32_e32 v19, v18
	s_nop 0
	v_add_u32_e32 v20, -1, v19
	v_add_u32_e32 v21, 1, v19
	v_fma_f32 v42, -v20, v19, v18
	v_fma_f32 v43, -v21, v19, v18
	v_cmp_ge_f32_e64 s[0:1], 0, v42
	s_nop 1
	v_cndmask_b32_e64 v19, v19, v20, s[0:1]
	v_cmp_lt_f32_e64 s[0:1], 0, v43
	s_nop 1
	v_cndmask_b32_e64 v19, v19, v21, s[0:1]
	v_mul_f32_e32 v20, 0x37800000, v19
	v_cndmask_b32_e32 v19, v19, v20, vcc
	v_cmp_class_f32_e32 vcc, v18, v13
	s_nop 1
	v_cndmask_b32_e32 v18, v19, v18, vcc
	v_div_scale_f32 v19, s[0:1], v18, v18, 1.0
	v_rcp_f32_e32 v21, v19
	v_div_scale_f32 v20, vcc, 1.0, v18, 1.0
	s_cselect_b64 s[0:1], -1, 0
	v_fma_f32 v42, -v19, v21, 1.0
	v_fmac_f32_e32 v21, v42, v21
	v_mul_f32_e32 v42, v20, v21
	v_fma_f32 v43, -v19, v42, v20
	v_fmac_f32_e32 v42, v43, v21
	v_fma_f32 v19, -v19, v42, v20
	v_div_fmas_f32 v19, v19, v21, v42
	v_div_fixup_f32 v42, v19, v18, 1.0
	v_pk_mul_f32 v[18:19], v[42:43], v[32:33] op_sel_hi:[0,1]
	v_pk_mul_f32 v[14:15], v[42:43], v[14:15] op_sel_hi:[0,1]
	v_pk_mul_f32 v[32:33], v[42:43], v[34:35] op_sel_hi:[0,1]
	v_pk_mul_f32 v[20:21], v[42:43], v[16:17] op_sel_hi:[0,1]
	s_waitcnt vmcnt(2)
	v_pk_mul_f32 v[16:17], v[14:15], v[66:67]
	v_pk_mul_f32 v[14:15], v[18:19], v[64:65]
	v_pk_mul_f32 v[20:21], v[20:21], v[62:63]
	v_pk_mul_f32 v[18:19], v[32:33], v[60:61]
	global_store_dwordx4 v[4:5], v[14:17], off
	global_store_dwordx4 v[4:5], v[18:21], off offset:16
	s_cmp_lt_u32 s9, 7
	s_mov_b32 s9, s10
	s_cselect_b64 s[10:11], -1, 0
	s_or_b64 s[10:11], s[20:21], s[10:11]
	v_pk_mul_f32 v[22:23], v[42:43], v[38:39] op_sel_hi:[0,1]
	v_pk_mul_f32 v[24:25], v[42:43], v[36:37] op_sel_hi:[0,1]
	s_and_b64 s[0:1], s[0:1], s[10:11]
	v_pk_mul_f32 v[26:27], v[42:43], v[30:31] op_sel_hi:[0,1]
	v_pk_mul_f32 v[28:29], v[42:43], v[40:41] op_sel_hi:[0,1]
	s_add_i32 s8, s8, s2
	s_andn2_b64 vcc, exec, s[0:1]
	s_nop 0
	v_pk_mul_f32 v[14:15], v[24:25], v[68:69]
	v_pk_mul_f32 v[16:17], v[22:23], v[70:71]
	v_pk_mul_f32 v[18:19], v[28:29], v[72:73]
	v_pk_mul_f32 v[20:21], v[26:27], v[74:75]
	global_store_dwordx4 v[4:5], v[14:17], off offset:2048
	global_store_dwordx4 v[4:5], v[18:21], off offset:2064
	v_lshl_add_u64 v[4:5], v[4:5], 0, s[6:7]
	s_cbranch_vccz .LBB0_1127
